# adds a straight-line pack-and-store epilogue for the plain bf16 GEMM (ukv) to the tile-order and squared-ReLU epilogue changes
# baseline (speedup 1.0000x reference)
;     __device__ __forceinline__ void operator()(const f32x4 (&acc)[2][2][4][2], const Unit& u, int wr, int wc, int fr_in, int fq_in) const {
;     ...
; #pragma unroll
;         for (int bj = 0; bj < 2; ++bj) {
;             const int c = col0 + bj * HALF;
;             f32x4 cs0 = {0.f, 0.f, 0.f, 0.f}, cs1 = cs0, bw0 = cs0, bw1 = cs0;
;             if (lnin) { const unsigned cb = (unsigned)c * 4u; cs0 = *(const f32x4*)((const char*)cs + cb); cs1 = *(const f32x4*)((const char*)cs + cb + 16u); bw0 = *(const f32x4*)((const char*)bw + cb); bw1 = *(const f32x4*)((const char*)bw + cb + 16u); }
.LBB0_287:
	s_cmp_eq_u32 s56, 0
	s_cbranch_scc1 .Lepi_bf16
	v_mov_b32_e32 v164, 0
	v_mov_b32_e32 v165, v164
	v_mov_b32_e32 v166, v164
	v_mov_b32_e32 v167, v164
	v_mov_b32_e32 v160, v164
	v_mov_b32_e32 v161, v164
	v_mov_b32_e32 v162, v164
	v_mov_b32_e32 v163, v164
	v_mov_b32_e32 v172, v164
	v_mov_b32_e32 v173, v164
	v_mov_b32_e32 v174, v164
	v_mov_b32_e32 v175, v164
	v_mov_b32_e32 v168, v164
	v_mov_b32_e32 v169, v164
	v_mov_b32_e32 v170, v164
	v_mov_b32_e32 v171, v164
	s_cmp_lt_i32 s56, 3
	s_cbranch_scc0 .LBB0_274

; __device__ __forceinline__ unsigned cvt_pk_bf16(float lo, float hi) { unsigned r; asm volatile("v_cvt_pk_bf16_f32 %0, %1, %2" : "=v"(r) : "v"(lo), "v"(hi)); return r; }
;     __device__ __forceinline__ void operator()(const f32x4 (&acc)[2][2][4][2], const Unit& u, int wr, int wc, int fr_in, int fq_in) const {
;     ...
;                         u32x4 w; w.x = cvt_pk_bf16(v0[0], v0[1]); w.y = cvt_pk_bf16(v0[2], v0[3]); w.z = cvt_pk_bf16(v1[0], v1[1]); w.w = cvt_pk_bf16(v1[2], v1[3]);
;                         { u32x4* dp = (u32x4*)((char*)Ob + (unsigned)(row * ldo + c) * 2u); if (mode == EM_RELU2) { asm volatile("global_store_dwordx4 %0, %1, %2 nt\n\ts_nop 1" :: "v"((unsigned)(row * ldo + c) * 2u), "v"(w), "s"(Ob) : "memory"); } else *dp = w; }
.Lepi_bf16:
	v_mul_lo_u32 v189, v236, s55
	v_add_lshl_u32 v222, v189, v232, 1
	s_lshl_b32 s0, s55, 5
	v_add_u32_e32 v223, s0, v222
	s_lshl_b32 s1, s55, 6
	v_add_u32_e32 v224, s1, v222
	s_add_i32 s1, s1, s0
	v_add_u32_e32 v225, s1, v222
	s_lshl_b32 s1, s55, 8
	v_add_u32_e32 v226, s1, v222
	v_add_u32_e32 v227, s1, v223
	v_add_u32_e32 v228, s1, v224
	v_add_u32_e32 v229, s1, v225
	v_cvt_pk_bf16_f32 v128, v124, v125
	v_cvt_pk_bf16_f32 v129, v126, v127
	v_cvt_pk_bf16_f32 v130, v120, v121
	v_cvt_pk_bf16_f32 v131, v122, v123
	global_store_dwordx4 v222, v[128:131], s[50:51]
	v_cvt_pk_bf16_f32 v132, v116, v117
	v_cvt_pk_bf16_f32 v133, v118, v119
	v_cvt_pk_bf16_f32 v134, v112, v113
	v_cvt_pk_bf16_f32 v135, v114, v115
	global_store_dwordx4 v223, v[132:135], s[50:51]
	v_cvt_pk_bf16_f32 v136, v108, v109
	v_cvt_pk_bf16_f32 v137, v110, v111
	v_cvt_pk_bf16_f32 v138, v104, v105
	v_cvt_pk_bf16_f32 v139, v106, v107
	global_store_dwordx4 v224, v[136:139], s[50:51]
	v_cvt_pk_bf16_f32 v140, v100, v101
	v_cvt_pk_bf16_f32 v141, v102, v103
	v_cvt_pk_bf16_f32 v142, v96, v97
	v_cvt_pk_bf16_f32 v143, v98, v99
	global_store_dwordx4 v225, v[140:143], s[50:51]
	v_cvt_pk_bf16_f32 v128, v60, v61
	v_cvt_pk_bf16_f32 v129, v62, v63
	v_cvt_pk_bf16_f32 v130, v56, v57
	v_cvt_pk_bf16_f32 v131, v58, v59
	global_store_dwordx4 v226, v[128:131], s[50:51]
	v_cvt_pk_bf16_f32 v132, v52, v53
	v_cvt_pk_bf16_f32 v133, v54, v55
	v_cvt_pk_bf16_f32 v134, v48, v49
	v_cvt_pk_bf16_f32 v135, v50, v51
	global_store_dwordx4 v227, v[132:135], s[50:51]
	v_cvt_pk_bf16_f32 v136, v44, v45
	v_cvt_pk_bf16_f32 v137, v46, v47
	v_cvt_pk_bf16_f32 v138, v40, v41
	v_cvt_pk_bf16_f32 v139, v42, v43
	global_store_dwordx4 v228, v[136:139], s[50:51]
	v_cvt_pk_bf16_f32 v140, v36, v37
	v_cvt_pk_bf16_f32 v141, v38, v39
	v_cvt_pk_bf16_f32 v142, v32, v33
	v_cvt_pk_bf16_f32 v143, v34, v35
	global_store_dwordx4 v229, v[140:143], s[50:51]
	v_cvt_pk_bf16_f32 v128, v92, v93
	v_cvt_pk_bf16_f32 v129, v94, v95
	v_cvt_pk_bf16_f32 v130, v88, v89
	v_cvt_pk_bf16_f32 v131, v90, v91
	global_store_dwordx4 v222, v[128:131], s[50:51] offset:256
	v_cvt_pk_bf16_f32 v132, v84, v85
	v_cvt_pk_bf16_f32 v133, v86, v87
	v_cvt_pk_bf16_f32 v134, v80, v81
	v_cvt_pk_bf16_f32 v135, v82, v83
	global_store_dwordx4 v223, v[132:135], s[50:51] offset:256
	v_cvt_pk_bf16_f32 v136, v76, v77
	v_cvt_pk_bf16_f32 v137, v78, v79
	v_cvt_pk_bf16_f32 v138, v72, v73
	v_cvt_pk_bf16_f32 v139, v74, v75
	global_store_dwordx4 v224, v[136:139], s[50:51] offset:256
	v_cvt_pk_bf16_f32 v140, v68, v69
	v_cvt_pk_bf16_f32 v141, v70, v71
	v_cvt_pk_bf16_f32 v142, v64, v65
	v_cvt_pk_bf16_f32 v143, v66, v67
	global_store_dwordx4 v225, v[140:143], s[50:51] offset:256
	v_cvt_pk_bf16_f32 v128, v28, v29
	v_cvt_pk_bf16_f32 v129, v30, v31
	v_cvt_pk_bf16_f32 v130, v24, v25
	v_cvt_pk_bf16_f32 v131, v26, v27
	global_store_dwordx4 v226, v[128:131], s[50:51] offset:256
	v_cvt_pk_bf16_f32 v132, v20, v21
	v_cvt_pk_bf16_f32 v133, v22, v23
	v_cvt_pk_bf16_f32 v134, v16, v17
	v_cvt_pk_bf16_f32 v135, v18, v19
	global_store_dwordx4 v227, v[132:135], s[50:51] offset:256
	v_cvt_pk_bf16_f32 v136, v12, v13
	v_cvt_pk_bf16_f32 v137, v14, v15
	v_cvt_pk_bf16_f32 v138, v8, v9
	v_cvt_pk_bf16_f32 v139, v10, v11
	global_store_dwordx4 v228, v[136:139], s[50:51] offset:256
	v_cvt_pk_bf16_f32 v140, v4, v5
	v_cvt_pk_bf16_f32 v141, v6, v7
	v_cvt_pk_bf16_f32 v142, v0, v1
	v_cvt_pk_bf16_f32 v143, v2, v3
	global_store_dwordx4 v229, v[140:143], s[50:51] offset:256
	s_branch .LBB0_736
